# sliding-window GQA mixer: next key tile K/V rows prefetched into spare registers one tile ahead; per-MFMA load waits removed
# baseline (speedup 1.0000x reference)
; #define LAS __attribute__((address_space(3)))
; template <int MODE>
; __device__ __forceinline__ void attn_wave(LAS unsigned char* lds, const bf16_t* qkv, bf16_t* Yout, const float* sinks, int wi) {
;     ...
;     const int qb = (MODE == MODE_A) ? (wi & 127) : (wi & 31), h = (MODE == MODE_A) ? ((wi >> 7) & 1) * 4 : ((wi >> 5) & 7), b = wi >> 8;
;     const int q0 = (MODE == MODE_A) ? qb * 16 : qb * 64;
;     constexpr int QSTEP = (MODE == MODE_A) ? 0 : 16, HSTEP = (MODE == MODE_A) ? 1 : 0;
;     const bf16_t* base = qkv + (size_t)b * SEQ * QP;
;     const bf16_t* qp = base + (MODE == MODE_A ? C_AQ + h * 64 : C_CQ + h * 64);
;     const bf16_t* kp = base + (MODE == MODE_A ? C_AK + (h >> 2) * 64 : C_CK + h * 64);
;     const bf16_t* vp = base + (MODE == MODE_A ? C_AV + (h >> 2) * 64 : C_CV + h * 64);
;     LAS unsigned char* Vs = lds + AW_VT + wid * ATT_TILE;
;     const LAS float* lutp = (const LAS float*)(lds + AW_LUT) + h * 128;
;     bf16x8 qf[NQT][2];
; #pragma unroll
;     for (int qt = 0; qt < NQT; ++qt)
; #pragma unroll
;         for (int ks = 0; ks < 2; ++ks) qf[qt][ks] = *(const bf16x8*)(qp + (size_t)(q0 + qt * QSTEP + c) * QP + qt * HSTEP * 64 + ks * 32 + g * 8);
;     f32x4 o[NQT][4];
; #pragma unroll
;     for (int qt = 0; qt < NQT; ++qt)
; #pragma unroll
;         for (int dt = 0; dt < 4; ++dt) o[qt][dt] = (f32x4){0.f, 0.f, 0.f, 0.f};
;     float mrun[NQT], lrun[NQT], carry[NQT];
; #pragma unroll
;     for (int qt = 0; qt < NQT; ++qt) { mrun[qt] = -1e30f; lrun[qt] = 0.f; carry[qt] = 0.f; }
;     const int kb_hi = (MODE == MODE_A) ? ((q0 + 15) >> 5) : ((q0 + 63) >> 5);
;     int kb_lo = 0;
;     if (MODE == MODE_A) { const int lo = q0 - 127; kb_lo = lo > 0 ? (lo >> 5) : 0; }
;     ...
;         const int k0 = kb * 32;
;         u32x4 vr[4];
; #pragma unroll
; __global__ void __launch_bounds__(512, 2) mega_fwd(Args a) {
;     ...
;                 unsigned v_ = 0u; if ((t1_ & 63) == 0) v_ = atomicAdd(qctr, 1u);
;                 const int it = (int)__builtin_amdgcn_readfirstlane(v_);
;                 if (it >= 1024 + 8192 + 8192) break;
;                 if (it < 1024) item_cmpk(BIG, Wb, hb, KC, it >> 3, it & 7);
;                 else if (it < 1024 + 8192) attn_wave<MODE_C>(lds, BIG, Yc, nullptr, it - 1024);
;                 else attn_wave<MODE_A>(lds, BIG, Ya, a.in[11] + l * 8, it - 1024 - 8192);
.LBB0_253:
	s_or_b64 exec, exec, s[0:1]
	v_readfirstlane_b32 s26, v1
	s_cmpk_gt_i32 s26, 0x43ff
	s_mov_b64 s[0:1], -1
	s_cbranch_scc1 .LBB0_248
	s_cmpk_gt_i32 s26, 0x3ff
	s_cbranch_scc0 .LBB0_348
	s_cmpk_gt_u32 s26, 0x23ff
	s_cbranch_scc0 .LBB0_335
	s_add_i32 s0, s26, 0xffffdc00
	s_lshl_b32 s4, s0, 4
	s_lshr_b32 s1, s26, 5
	s_and_b32 s9, s4, 0x7f0
	s_lshl_b32 s0, s0, 3
	s_and_b32 s11, s1, 4
	s_and_b32 s10, s0, 0xf800
	s_add_i32 s0, s9, 0xffffff81
	s_lshl_b32 s8, s11, 6
	s_bfe_u32 s5, s4, 0x60005
	s_lshr_b32 s0, s0, 5
	v_mov_b32_e32 v1, v214
	s_cmpk_gt_u32 s9, 0x7f
	s_cselect_b32 s13, s0, 0
	v_bfe_u32 v2, v1, 4, 2
	v_readfirstlane_b32 s6, v1
	v_and_b32_e32 v154, 15, v1
	s_mov_b64 s[0:1], -1
	s_cmp_ge_u32 s5, s13
	v_lshlrev_b32_e32 v160, 2, v2
	s_cbranch_scc0 .LBB0_332
	s_mul_i32 s7, s10, 0x1c30
	v_readlane_b32 s0, v252, 52
	v_readlane_b32 s1, v252, 53
	s_add_u32 s0, s0, s7
	s_addc_u32 s1, s1, 0
	s_lshl_b32 s19, s8, 1
	v_or_b32_e32 v8, s9, v154
	s_add_u32 s0, s0, s19
	v_mul_u32_u24_e32 v8, 0xe18, v8
	s_addc_u32 s1, s1, 0
	v_lshlrev_b32_e32 v8, 1, v8
	v_mov_b32_e32 v9, v0
	v_lshl_add_u64 v[8:9], s[0:1], 0, v[8:9]
	v_lshlrev_b32_e32 v10, 4, v2
	v_mov_b32_e32 v11, v0
	v_lshl_add_u64 v[8:9], v[8:9], 0, v[10:11]
	global_load_dwordx4 v[72:75], v[8:9], off
	global_load_dwordx4 v[76:79], v[8:9], off offset:64
	global_load_dwordx4 v[80:83], v[8:9], off offset:128
	global_load_dwordx4 v[84:87], v[8:9], off offset:192
	global_load_dwordx4 v[88:91], v[8:9], off offset:256
	global_load_dwordx4 v[92:95], v[8:9], off offset:320
	global_load_dwordx4 v[96:99], v[8:9], off offset:384
	global_load_dwordx4 v[100:103], v[8:9], off offset:448
	s_lshr_b32 s0, s6, 6
	s_mulk_i32 s0, 0x2400
	v_lshlrev_b32_e32 v8, 4, v1
	s_add_i32 s0, s0, 0
	v_and_b32_e32 v8, 0x70, v8
	s_lshl_b32 s44, s5, 5
	v_add_u32_e32 v12, s0, v8
	v_mov_b32_e32 v11, s0
	s_sub_i32 s0, s9, s44
	v_lshlrev_b32_e32 v155, 2, v2
	v_lshrrev_b32_e32 v2, 2, v154
	s_sub_i32 s45, s0, 31
	s_lshl_b32 s0, s4, 2
	v_and_b32_e32 v3, 63, v1
	v_or_b32_e32 v2, v155, v2
	s_and_b32 s0, s0, 0x1fc0
	v_mad_u32_u24 v13, v2, s84, v11
	v_lshrrev_b32_e32 v2, 3, v3
	v_lshl_or_b32 v3, v154, 2, s0
	v_sub_u32_e32 v3, v3, v10
	s_lshl_b32 s0, s5, 7
	v_subrev_u32_e32 v3, s0, v3
	v_add_u32_e32 v165, 0, v3
	v_add_u32_e32 v3, s9, v154
	v_lshlrev_b32_e32 v9, 3, v1
	v_sub_u32_e32 v3, v3, v155
	v_or_b32_e32 v16, s44, v2
	v_and_b32_e32 v14, 24, v9
	v_subrev_u32_e32 v3, s44, v3
	v_mov_b32_e32 v9, v0
	v_or_b32_e32 v10, 8, v16
	v_mul_u32_u24_e32 v15, 0x90, v2
	v_lshl_add_u32 v167, v3, 2, 0
	v_mad_u64_u32 v[2:3], s[0:1], v16, s85, v[8:9]
	v_or_b32_e32 v8, 0xc000500, v8
	v_mul_u32_u24_e32 v10, 0x1c30, v10
	v_mov_b32_e32 v11, v0
	v_lshl_add_u64 v[144:145], v[8:9], 0, v[10:11]
	v_or_b32_e32 v10, 16, v16
	v_mul_u32_u24_e32 v10, 0x1c30, v10
	s_mov_b64 s[0:1], 0xc000500
	v_lshl_add_u64 v[146:147], v[8:9], 0, v[10:11]
	v_or_b32_e32 v10, 24, v16
	s_lshl_b32 s19, s11, 9
	s_or_b32 s27, s9, 15
	s_add_i32 s36, s5, 1
	v_lshl_add_u64 v[2:3], v[2:3], 0, s[0:1]
	s_and_b32 s0, s26, 0x80
	v_mul_u32_u24_e32 v10, 0x1c30, v10
	s_add_u32 s0, s7, s0
	v_readlane_b32 s48, v252, 4
	v_lshl_add_u64 v[148:149], v[8:9], 0, v[10:11]
	v_and_b32_e32 v8, 48, v1
	v_or_b32_e32 v10, s44, v154
	s_addc_u32 s1, 0, 0
	v_readlane_b32 s52, v252, 8
	v_mad_u64_u32 v[150:151], s[4:5], v10, s85, v[8:9]
	v_or_b32_e32 v10, 16, v10
	v_readlane_b32 s53, v252, 9
	s_add_u32 s0, s52, s0
	v_mul_u32_u24_e32 v10, 0x1c30, v10
	v_mov_b32_e32 v156, 0
	v_sub_u32_e32 v166, v154, v155
	s_addc_u32 s1, s53, s1
	v_lshl_add_u64 v[152:153], v[8:9], 0, v[10:11]
	s_brev_b32 s4, 48
	v_lshl_add_u64 v[176:177], s[0:1], 0, v[2:3]
	v_lshl_add_u64 v[180:181], s[0:1], 0, v[144:145]
	v_lshl_add_u64 v[184:185], s[0:1], 0, v[146:147]
	v_lshl_add_u64 v[188:189], s[0:1], 0, v[148:149]
	v_lshl_add_u64 v[196:197], s[0:1], 0, v[150:151]
	v_lshl_add_u64 v[200:201], s[0:1], 0, v[152:153]
	global_load_dwordx4 v[176:179], v[176:177], off
	global_load_dwordx4 v[180:183], v[180:181], off
	global_load_dwordx4 v[184:187], v[184:185], off
	global_load_dwordx4 v[188:191], v[188:189], off
	v_add_co_u32_e32 v196, vcc, s4, v196
	v_addc_co_u32_e32 v197, vcc, 0, v197, vcc
	v_add_co_u32_e32 v200, vcc, s4, v200
	v_addc_co_u32_e32 v201, vcc, 0, v201, vcc
	global_load_dwordx4 v[192:195], v[196:197], off offset:1024
	global_load_dwordx4 v[196:199], v[196:197], off offset:1088
	global_load_dwordx4 v[204:207], v[200:201], off offset:1024
	global_load_dwordx4 v[200:203], v[200:201], off offset:1088
	v_mov_b32_e32 v157, 0xf149f2ca
	v_add_u32_e32 v168, v12, v15
	v_add_u32_e32 v169, v13, v14
	v_mov_b32_e32 v159, 0xf149f2ca
	v_mov_b32_e32 v162, 0xf149f2ca
	v_mov_b32_e32 v163, 0xf149f2ca
	v_mov_b32_e32 v158, 0
	v_mov_b32_e32 v161, 0
	v_mov_b32_e32 v164, 0
	v_mov_b32_e32 v68, 0
	v_mov_b32_e32 v69, v156
	v_mov_b32_e32 v70, v156
	v_mov_b32_e32 v71, v156
	v_mov_b32_e32 v64, 0
	v_mov_b32_e32 v65, v156
	v_mov_b32_e32 v66, v156
	v_mov_b32_e32 v67, v156
	v_mov_b32_e32 v60, 0
	v_mov_b32_e32 v61, v156
	v_mov_b32_e32 v62, v156
	v_mov_b32_e32 v63, v156
	v_mov_b32_e32 v56, 0
	v_mov_b32_e32 v57, v156
	v_mov_b32_e32 v58, v156
	v_mov_b32_e32 v59, v156
	v_mov_b32_e32 v40, 0
	v_mov_b32_e32 v41, v156
	v_mov_b32_e32 v42, v156
	v_mov_b32_e32 v43, v156
	v_mov_b32_e32 v44, 0
	v_mov_b32_e32 v45, v156
	v_mov_b32_e32 v46, v156
	v_mov_b32_e32 v47, v156
	v_mov_b32_e32 v48, 0
	v_mov_b32_e32 v49, v156
	v_mov_b32_e32 v50, v156
	v_mov_b32_e32 v51, v156
	v_mov_b32_e32 v52, 0
	v_mov_b32_e32 v53, v156
	v_mov_b32_e32 v54, v156
	v_mov_b32_e32 v55, v156
	v_mov_b32_e32 v24, 0
	v_mov_b32_e32 v25, v156
	v_mov_b32_e32 v26, v156
	v_mov_b32_e32 v27, v156
	v_mov_b32_e32 v28, 0
	v_mov_b32_e32 v29, v156
	v_mov_b32_e32 v30, v156
	v_mov_b32_e32 v31, v156
	v_mov_b32_e32 v32, 0
	v_mov_b32_e32 v33, v156
	v_mov_b32_e32 v34, v156
	v_mov_b32_e32 v35, v156
	v_mov_b32_e32 v36, 0
	v_mov_b32_e32 v37, v156
	v_mov_b32_e32 v38, v156
	v_mov_b32_e32 v39, v156
	v_mov_b32_e32 v8, 0
	v_mov_b32_e32 v9, v156
	v_mov_b32_e32 v10, v156
	v_mov_b32_e32 v11, v156
	v_mov_b32_e32 v12, 0
	v_mov_b32_e32 v13, v156
	v_mov_b32_e32 v14, v156
	v_mov_b32_e32 v15, v156
	v_mov_b32_e32 v16, 0
	v_mov_b32_e32 v17, v156
	v_mov_b32_e32 v18, v156
	v_mov_b32_e32 v19, v156
	v_mov_b32_e32 v20, 0
	v_mov_b32_e32 v21, v156
	v_mov_b32_e32 v22, v156
	v_mov_b32_e32 v23, v156
	s_movk_i32 s15, 0x80
	v_readlane_b32 s49, v252, 5
	v_readlane_b32 s50, v252, 6
	v_readlane_b32 s51, v252, 7
	v_readlane_b32 s54, v252, 10
	v_readlane_b32 s55, v252, 11
	s_branch .LBB0_260

; #define LAS __attribute__((address_space(3)))
; __device__ __forceinline__ bf16x8 vfrag(const LAS unsigned char* p) { const v4i16_t a = tr_read(p), b = tr_read(p + 16 * KPB); return (bf16x8){a[0], a[1], a[2], a[3], b[0], b[1], b[2], b[3]}; }
; template <int MODE>
; __device__ __forceinline__ void attn_wave(LAS unsigned char* lds, const bf16_t* qkv, bf16_t* Yout, const float* sinks, int wi) {
;     ...
;         const int k0 = kb * 32;
;         u32x4 vr[4];
; #pragma unroll
;         for (int i = 0; i < 4; ++i) { const int e = lane + 64 * i; vr[i] = *(const u32x4*)(vp + (size_t)(k0 + (e >> 3)) * QP + (e & 7) * 8); }
;         bf16x8 kf[2][2];
; #pragma unroll
;         for (int nt = 0; nt < 2; ++nt)
; #pragma unroll
;             for (int ks = 0; ks < 2; ++ks) kf[nt][ks] = *(const bf16x8*)(kp + (size_t)(k0 + 16 * nt + c) * QP + ks * 32 + g * 8);
; #pragma unroll
;         for (int i = 0; i < 4; ++i) { const int e = lane + 64 * i; *(LAS u32x4*)(Vs + (e >> 3) * KPB + (e & 7) * 16) = vr[i]; }
;         bf16x8 vfr[4];
;         { const LAS unsigned char* vb = Vs + (4 * g + (c >> 2)) * KPB + (c & 3) * 8;
; #pragma unroll
;           for (int dt = 0; dt < 4; ++dt) vfr[dt] = vfrag(vb + dt * 32); }
;         __builtin_amdgcn_sched_barrier(0);
; #pragma unroll
;         for (int qt = 0; qt < NQT; ++qt) {
;             bool live = (k0 <= q0 + QSTEP * qt + 15);
;             if (MODE == MODE_A) live = live && (q0 + QSTEP * qt - (k0 + 31) < 128);
.LBB0_260:
	s_waitcnt vmcnt(0)
	s_waitcnt lgkmcnt(0)
	ds_write_b128 v168, v[176:179]
	ds_write_b128 v168, v[180:183] offset:1152
	ds_write_b128 v168, v[184:187] offset:2304
	ds_write_b128 v168, v[188:191] offset:3456
	v_mov_b64_e32 v[120:121], v[192:193]
	v_mov_b64_e32 v[122:123], v[194:195]
	v_mov_b64_e32 v[124:125], v[196:197]
	v_mov_b64_e32 v[126:127], v[198:199]
	v_mov_b64_e32 v[128:129], v[200:201]
	v_mov_b64_e32 v[130:131], v[202:203]
	v_mov_b64_e32 v[132:133], v[204:205]
	v_mov_b64_e32 v[134:135], v[206:207]
	ds_read_b64_tr_b16 v[116:117], v169
	ds_read_b64_tr_b16 v[112:113], v169 offset:32
	ds_read_b64_tr_b16 v[108:109], v169 offset:64
	ds_read_b64_tr_b16 v[104:105], v169 offset:96
	ds_read_b64_tr_b16 v[118:119], v169 offset:2304
	ds_read_b64_tr_b16 v[114:115], v169 offset:2336
	ds_read_b64_tr_b16 v[110:111], v169 offset:2368
	ds_read_b64_tr_b16 v[106:107], v169 offset:2400
	s_add_i32 s6, s36, -1
	s_cmp_gt_i32 s6, s13
	s_cbranch_scc0 .Lapre_skip
	s_add_u32 s6, s0, 0xfffc7a00
	s_addc_u32 s7, s1, -1
	s_brev_b32 s4, 48
	v_lshl_add_u64 v[176:177], s[6:7], 0, v[2:3]
	v_lshl_add_u64 v[180:181], s[6:7], 0, v[144:145]
	v_lshl_add_u64 v[184:185], s[6:7], 0, v[146:147]
	v_lshl_add_u64 v[188:189], s[6:7], 0, v[148:149]
	v_lshl_add_u64 v[196:197], s[6:7], 0, v[150:151]
	v_lshl_add_u64 v[200:201], s[6:7], 0, v[152:153]
	global_load_dwordx4 v[176:179], v[176:177], off
	global_load_dwordx4 v[180:183], v[180:181], off
	global_load_dwordx4 v[184:187], v[184:185], off
	global_load_dwordx4 v[188:191], v[188:189], off
	v_add_co_u32_e32 v196, vcc, s4, v196
	v_addc_co_u32_e32 v197, vcc, 0, v197, vcc
	v_add_co_u32_e32 v200, vcc, s4, v200
	v_addc_co_u32_e32 v201, vcc, 0, v201, vcc
	global_load_dwordx4 v[192:195], v[196:197], off offset:1024
	global_load_dwordx4 v[196:199], v[196:197], off offset:1088
	global_load_dwordx4 v[204:207], v[200:201], off offset:1024
	global_load_dwordx4 v[200:203], v[200:201], off offset:1088
.Lapre_skip:
	s_cmp_le_i32 s44, s27
	s_cselect_b64 s[4:5], -1, 0
	s_cmpk_lt_i32 s45, 0x80
	s_cselect_b64 s[6:7], -1, 0
	s_and_b64 s[6:7], s[4:5], s[6:7]
	v_cndmask_b32_e64 v136, 0, 1, s[6:7]
	v_add_u32_e32 v170, s45, v166
	v_cmp_ne_u32_e64 s[4:5], 1, v136
	s_andn2_b64 vcc, exec, s[6:7]
	v_add_u32_e32 v171, 31, v170
	s_cbranch_vccz .LBB0_264
	s_and_b64 vcc, exec, s[4:5]
	s_cbranch_vccz .LBB0_281

; #define MFMA16(a, b, c) __builtin_amdgcn_mfma_f32_16x16x32_bf16((a), (b), (c), 0, 0, 0)
; template <int MODE>
; __device__ __forceinline__ void attn_wave(LAS unsigned char* lds, const bf16_t* qkv, bf16_t* Yout, const float* sinks, int wi) {
;     ...
;             f32x4 s[2];
; #pragma unroll
;             for (int nt = 0; nt < 2; ++nt) { f32x4 z = (f32x4){0.f, 0.f, 0.f, 0.f}; z = MFMA16(kf[nt][0], qf[qt][0], z); s[nt] = MFMA16(kf[nt][1], qf[qt][1], z); }
;             const int dbase = q0 + QSTEP * qt + c - k0 - 4 * g;
;             if (MODE == MODE_A) {
;                 float mx = -1e30f;
; #pragma unroll
;                 for (int nt = 0; nt < 2; ++nt)
; #pragma unroll
;                     for (int j = 0; j < 4; ++j) { const int dist = dbase - (16 * nt + j); const bool valid = (unsigned)dist < 128u;
;                         const float bias2 = lutp[qt * HSTEP * 128 + (dist & 127)];
;                         const float lg = valid ? (s[nt][j] * C1 + bias2) : -1e30f; s[nt][j] = lg; mx = fmaxf(mx, lg); }
;                 mx = fmaxf(mx, __shfl_xor(mx, 16)); mx = fmaxf(mx, __shfl_xor(mx, 32));
;                 const float mnew = fmaxf(mrun[qt], mx); const float alpha = __builtin_amdgcn_exp2f(mrun[qt] - mnew); mrun[qt] = mnew;
;                 float ps = 0.f;
; #pragma unroll
;                 for (int nt = 0; nt < 2; ++nt)
; #pragma unroll
;                     for (int j = 0; j < 4; ++j) { const float p = __builtin_amdgcn_exp2f(s[nt][j] - mnew); s[nt][j] = p; ps += p; }
;                 lrun[qt] = lrun[qt] * alpha + ps;
; #pragma unroll
;                 for (int dt = 0; dt < 4; ++dt) o[qt][dt] = o[qt][dt] * alpha;
;             } else {
;                 float lk[2][4], c4[2];
; #pragma unroll
;                 for (int nt = 0; nt < 2; ++nt) { c4[nt] = 0.f;
; #pragma unroll
;                     for (int j = 0; j < 4; ++j) { const bool valid = (dbase - (16 * nt + j)) > 0; const float z = s[nt][j] * C1;
;                         const float e = __builtin_amdgcn_exp2f(-fabsf(z));
;                         const float sp = fmaxf(z, 0.f) + __builtin_amdgcn_logf(1.f + e);
;                         lk[nt][j] = valid ? -sp : 0.f; s[nt][j] = valid ? (z - sp) : -1e30f; c4[nt] += lk[nt][j]; } }
;                 float after = 0.f;
; #pragma unroll
;     ...
;                     const float v1 = __shfl_xor(c4[nt], 16), v2 = __shfl_xor(c4[nt], 32), v3 = __shfl_xor(c4[nt], 48);
.LBB0_264:
	v_mfma_f32_16x16x32_bf16 v[136:139], v[120:123], v[72:75], 0
	v_mfma_f32_16x16x32_bf16 v[140:143], v[124:127], v[76:79], v[136:139]
	v_mfma_f32_16x16x32_bf16 v[136:139], v[132:135], v[72:75], 0
	v_mfma_f32_16x16x32_bf16 v[136:139], v[128:131], v[76:79], v[136:139]
	v_add_u32_e32 v228, s19, v167
	v_add_u32_e32 v228, 0x12000, v228
	ds_read_b32 v228, v228
	v_add_u32_e32 v229, s19, v165
	v_add_u32_e32 v229, 0x11ffc, v229
	ds_read_b32 v229, v229
	v_add_u32_e32 v230, s19, v165
	v_add_u32_e32 v230, 0x11ff8, v230
	ds_read_b32 v230, v230
	v_add_u32_e32 v231, s19, v165
	v_add_u32_e32 v231, 0x11ff4, v231
	ds_read_b32 v231, v231
	v_add_u32_e32 v232, s19, v165
	v_add_u32_e32 v232, 0x11fc0, v232
	ds_read_b32 v232, v232
	v_add_u32_e32 v233, s19, v165
	v_add_u32_e32 v233, 0x11fbc, v233
	ds_read_b32 v233, v233
	v_add_u32_e32 v234, s19, v165
	v_add_u32_e32 v234, 0x11fb8, v234
	ds_read_b32 v234, v234
	v_add_u32_e32 v235, s19, v165
	v_add_u32_e32 v235, 0x11fb4, v235
	ds_read_b32 v235, v235
	s_waitcnt lgkmcnt(0)
	v_cmp_gt_u32_e32 vcc, s15, v171
	v_fmac_f32_e32 v228, 0x3e38aa3b, v140
	s_nop 0
	v_cndmask_b32_e32 v173, v226, v228, vcc
	v_add_u32_e32 v236, 30, v170
	v_cmp_gt_u32_e32 vcc, s15, v236
	v_fmac_f32_e32 v229, 0x3e38aa3b, v141
	s_nop 0
	v_cndmask_b32_e32 v172, v226, v229, vcc
	v_add_u32_e32 v236, 29, v170
	v_cmp_gt_u32_e32 vcc, s15, v236
	v_fmac_f32_e32 v230, 0x3e38aa3b, v142
	s_nop 0
	v_cndmask_b32_e32 v141, v226, v230, vcc
	v_add_u32_e32 v236, 28, v170
	v_cmp_gt_u32_e32 vcc, s15, v236
	v_fmac_f32_e32 v231, 0x3e38aa3b, v143
	s_nop 0
	v_cndmask_b32_e32 v140, v226, v231, vcc
	v_add_u32_e32 v236, 15, v170
	v_cmp_gt_u32_e32 vcc, s15, v236
	v_fmac_f32_e32 v232, 0x3e38aa3b, v136
	s_nop 0
	v_cndmask_b32_e32 v143, v226, v232, vcc
	v_add_u32_e32 v236, 14, v170
	v_cmp_gt_u32_e32 vcc, s15, v236
	v_fmac_f32_e32 v233, 0x3e38aa3b, v137
	s_nop 0
	v_cndmask_b32_e32 v142, v226, v233, vcc
	v_add_u32_e32 v236, 13, v170
	v_cmp_gt_u32_e32 vcc, s15, v236
	v_fmac_f32_e32 v234, 0x3e38aa3b, v138
	s_nop 0
	v_cndmask_b32_e32 v137, v226, v234, vcc
	v_add_u32_e32 v236, 12, v170
	v_cmp_gt_u32_e32 vcc, s15, v236
	v_fmac_f32_e32 v235, 0x3e38aa3b, v139
	s_nop 0
	v_cndmask_b32_e32 v136, v226, v235, vcc
	v_max3_f32 v138, v173, s86, v172
	v_max3_f32 v138, v138, v141, v140
	v_cmp_lt_i32_e32 vcc, v223, v218
	v_max3_f32 v138, v138, v143, v142
	v_max3_f32 v138, v138, v137, v136
	v_cndmask_b32_e32 v139, v217, v223, vcc
	v_lshlrev_b32_e32 v139, 2, v139
	ds_bpermute_b32 v139, v139, v138
	v_cmp_lt_i32_e32 vcc, v224, v218
	s_waitcnt lgkmcnt(0)
	v_max_f32_e32 v139, v139, v139
	v_max_f32_e32 v138, v138, v139
	v_cndmask_b32_e32 v139, v217, v224, vcc
	v_lshlrev_b32_e32 v139, 2, v139
	ds_bpermute_b32 v139, v139, v138
	s_waitcnt lgkmcnt(0)
	v_max3_f32 v174, v163, v138, v139
	v_sub_f32_e32 v139, v173, v174
	v_exp_f32_e32 v139, v139
	v_sub_f32_e32 v172, v172, v174
	v_exp_f32_e32 v172, v172
	v_sub_f32_e32 v141, v141, v174
	v_exp_f32_e32 v141, v141
	v_sub_f32_e32 v140, v140, v174
	v_exp_f32_e32 v140, v140
	v_sub_f32_e32 v143, v143, v174
	v_sub_f32_e32 v138, v163, v174
	v_add_f32_e32 v163, 0, v139
	v_exp_f32_e32 v143, v143
	v_sub_f32_e32 v142, v142, v174
	v_add_f32_e32 v163, v172, v163
	v_exp_f32_e32 v142, v142
	v_sub_f32_e32 v137, v137, v174
	v_add_f32_e32 v163, v141, v163
	v_exp_f32_e32 v173, v137
	v_add_f32_e32 v163, v140, v163
	v_add_f32_e32 v163, v143, v163
	v_add_f32_e32 v163, v142, v163
	v_sub_f32_e32 v136, v136, v174
	v_add_f32_e32 v137, v173, v163
	v_exp_f32_e32 v163, v136
	v_exp_f32_e32 v136, v138
	v_cvt_pk_bf16_f32 v138, v143, v142
	v_add_f32_e32 v175, v163, v137
	v_fmac_f32_e32 v175, v164, v136
	v_pk_mul_f32 v[58:59], v[58:59], v[136:137] op_sel_hi:[1,0]
	v_pk_mul_f32 v[56:57], v[56:57], v[136:137] op_sel_hi:[1,0]
	v_pk_mul_f32 v[62:63], v[62:63], v[136:137] op_sel_hi:[1,0]
	v_pk_mul_f32 v[60:61], v[60:61], v[136:137] op_sel_hi:[1,0]
	v_pk_mul_f32 v[66:67], v[66:67], v[136:137] op_sel_hi:[1,0]
	v_pk_mul_f32 v[64:65], v[64:65], v[136:137] op_sel_hi:[1,0]
	v_pk_mul_f32 v[70:71], v[70:71], v[136:137] op_sel_hi:[1,0]
	v_pk_mul_f32 v[68:69], v[68:69], v[136:137] op_sel_hi:[1,0]
	v_cvt_pk_bf16_f32 v136, v139, v172
	v_cvt_pk_bf16_f32 v137, v141, v140
	v_cvt_pk_bf16_f32 v139, v173, v163
	v_mov_b32_e32 v164, v175
	v_mov_b32_e32 v163, v174
	v_mfma_f32_16x16x32_bf16 v[56:59], v[116:119], v[136:139], v[56:59]
	v_mfma_f32_16x16x32_bf16 v[60:63], v[112:115], v[136:139], v[60:63]
	v_mfma_f32_16x16x32_bf16 v[64:67], v[108:111], v[136:139], v[64:67]
	v_mfma_f32_16x16x32_bf16 v[68:71], v[104:107], v[136:139], v[68:71]
	s_and_b64 vcc, exec, s[4:5]
	s_cbranch_vccnz .LBB0_262
; #define MFMA16(a, b, c) __builtin_amdgcn_mfma_f32_16x16x32_bf16((a), (b), (c), 0, 0, 0)
; template <int MODE>
; __device__ __forceinline__ void attn_wave(LAS unsigned char* lds, const bf16_t* qkv, bf16_t* Yout, const float* sinks, int wi) {
;     ...
;             f32x4 s[2];
; #pragma unroll
;             for (int nt = 0; nt < 2; ++nt) { f32x4 z = (f32x4){0.f, 0.f, 0.f, 0.f}; z = MFMA16(kf[nt][0], qf[qt][0], z); s[nt] = MFMA16(kf[nt][1], qf[qt][1], z); }
;             const int dbase = q0 + QSTEP * qt + c - k0 - 4 * g;
;             if (MODE == MODE_A) {
;                 float mx = -1e30f;
; #pragma unroll
;                 for (int nt = 0; nt < 2; ++nt)
; #pragma unroll
;                     for (int j = 0; j < 4; ++j) { const int dist = dbase - (16 * nt + j); const bool valid = (unsigned)dist < 128u;
;                         const float bias2 = lutp[qt * HSTEP * 128 + (dist & 127)];
;                         const float lg = valid ? (s[nt][j] * C1 + bias2) : -1e30f; s[nt][j] = lg; mx = fmaxf(mx, lg); }
;                 mx = fmaxf(mx, __shfl_xor(mx, 16)); mx = fmaxf(mx, __shfl_xor(mx, 32));
;                 const float mnew = fmaxf(mrun[qt], mx); const float alpha = __builtin_amdgcn_exp2f(mrun[qt] - mnew); mrun[qt] = mnew;
;                 float ps = 0.f;
; #pragma unroll
;                 for (int nt = 0; nt < 2; ++nt)
; #pragma unroll
;                     for (int j = 0; j < 4; ++j) { const float p = __builtin_amdgcn_exp2f(s[nt][j] - mnew); s[nt][j] = p; ps += p; }
;                 lrun[qt] = lrun[qt] * alpha + ps;
; #pragma unroll
;                 for (int dt = 0; dt < 4; ++dt) o[qt][dt] = o[qt][dt] * alpha;
;             } else {
;                 float lk[2][4], c4[2];
; #pragma unroll
;                 for (int nt = 0; nt < 2; ++nt) { c4[nt] = 0.f;
; #pragma unroll
;                     for (int j = 0; j < 4; ++j) { const bool valid = (dbase - (16 * nt + j)) > 0; const float z = s[nt][j] * C1;
;                         const float e = __builtin_amdgcn_exp2f(-fabsf(z));
;                         const float sp = fmaxf(z, 0.f) + __builtin_amdgcn_logf(1.f + e);
;                         lk[nt][j] = valid ? -sp : 0.f; s[nt][j] = valid ? (z - sp) : -1e30f; c4[nt] += lk[nt][j]; } }
;                 float after = 0.f;
; #pragma unroll
;     ...
;                     const float v1 = __shfl_xor(c4[nt], 16), v2 = __shfl_xor(c4[nt], 32), v3 = __shfl_xor(c4[nt], 48);
.LBB0_281:
	v_mfma_f32_16x16x32_bf16 v[136:139], v[120:123], v[80:83], 0
	v_mfma_f32_16x16x32_bf16 v[140:143], v[124:127], v[84:87], v[136:139]
	v_mfma_f32_16x16x32_bf16 v[136:139], v[132:135], v[80:83], 0
	v_mfma_f32_16x16x32_bf16 v[136:139], v[128:131], v[84:87], v[136:139]
	v_add_u32_e32 v228, s19, v167
	v_add_u32_e32 v228, 0x12200, v228
	ds_read_b32 v228, v228
	v_add_u32_e32 v229, s19, v167
	v_add_u32_e32 v229, 0x121fc, v229
	ds_read_b32 v229, v229
	v_add_u32_e32 v230, s19, v167
	v_add_u32_e32 v230, 0x121f8, v230
	ds_read_b32 v230, v230
	v_add_u32_e32 v231, s19, v167
	v_add_u32_e32 v231, 0x121f4, v231
	ds_read_b32 v231, v231
	v_add_u32_e32 v232, s19, v167
	v_add_u32_e32 v232, 0x121c0, v232
	ds_read_b32 v232, v232
	v_add_u32_e32 v233, s19, v165
	v_add_u32_e32 v233, 0x121bc, v233
	ds_read_b32 v233, v233
	v_add_u32_e32 v234, s19, v165
	v_add_u32_e32 v234, 0x121b8, v234
	ds_read_b32 v234, v234
	v_add_u32_e32 v235, s19, v165
	v_add_u32_e32 v235, 0x121b4, v235
	ds_read_b32 v235, v235
	s_waitcnt lgkmcnt(0)
	v_cmp_gt_u32_e32 vcc, s15, v171
	v_fmac_f32_e32 v228, 0x3e38aa3b, v140
	s_nop 0
	v_cndmask_b32_e32 v173, v226, v228, vcc
	v_add_u32_e32 v236, 30, v170
	v_cmp_gt_u32_e32 vcc, s15, v236
	v_fmac_f32_e32 v229, 0x3e38aa3b, v141
	s_nop 0
	v_cndmask_b32_e32 v172, v226, v229, vcc
	v_add_u32_e32 v236, 29, v170
	v_cmp_gt_u32_e32 vcc, s15, v236
	v_fmac_f32_e32 v230, 0x3e38aa3b, v142
	s_nop 0
	v_cndmask_b32_e32 v141, v226, v230, vcc
	v_add_u32_e32 v236, 28, v170
	v_cmp_gt_u32_e32 vcc, s15, v236
	v_fmac_f32_e32 v231, 0x3e38aa3b, v143
	s_nop 0
	v_cndmask_b32_e32 v140, v226, v231, vcc
	v_add_u32_e32 v236, 15, v170
	v_cmp_gt_u32_e32 vcc, s15, v236
	v_fmac_f32_e32 v232, 0x3e38aa3b, v136
	s_nop 0
	v_cndmask_b32_e32 v143, v226, v232, vcc
	v_add_u32_e32 v236, 14, v170
	v_cmp_gt_u32_e32 vcc, s15, v236
	v_fmac_f32_e32 v233, 0x3e38aa3b, v137
	s_nop 0
	v_cndmask_b32_e32 v142, v226, v233, vcc
	v_add_u32_e32 v236, 13, v170
	v_cmp_gt_u32_e32 vcc, s15, v236
	v_fmac_f32_e32 v234, 0x3e38aa3b, v138
	s_nop 0
	v_cndmask_b32_e32 v137, v226, v234, vcc
	v_add_u32_e32 v236, 12, v170
	v_cmp_gt_u32_e32 vcc, s15, v236
	v_fmac_f32_e32 v235, 0x3e38aa3b, v139
	s_nop 0
	v_cndmask_b32_e32 v136, v226, v235, vcc
	v_max3_f32 v138, v173, s86, v172
	v_max3_f32 v138, v138, v141, v140
	v_cmp_lt_i32_e32 vcc, v223, v218
	v_max3_f32 v138, v138, v143, v142
	v_max3_f32 v138, v138, v137, v136
	v_cndmask_b32_e32 v139, v217, v223, vcc
	v_lshlrev_b32_e32 v139, 2, v139
	ds_bpermute_b32 v139, v139, v138
	v_cmp_lt_i32_e32 vcc, v224, v218
	s_waitcnt lgkmcnt(0)
	v_max_f32_e32 v139, v139, v139
	v_max_f32_e32 v138, v138, v139
	v_cndmask_b32_e32 v139, v217, v224, vcc
	v_lshlrev_b32_e32 v139, 2, v139
	ds_bpermute_b32 v139, v139, v138
	s_waitcnt lgkmcnt(0)
	v_max3_f32 v174, v162, v138, v139
	v_sub_f32_e32 v139, v173, v174
	v_exp_f32_e32 v139, v139
	v_sub_f32_e32 v172, v172, v174
	v_exp_f32_e32 v172, v172
	v_sub_f32_e32 v141, v141, v174
	v_exp_f32_e32 v141, v141
	v_sub_f32_e32 v140, v140, v174
	v_exp_f32_e32 v140, v140
	v_sub_f32_e32 v143, v143, v174
	v_sub_f32_e32 v138, v162, v174
	v_add_f32_e32 v162, 0, v139
	v_exp_f32_e32 v143, v143
	v_sub_f32_e32 v142, v142, v174
	v_add_f32_e32 v162, v172, v162
	v_exp_f32_e32 v142, v142
	v_sub_f32_e32 v137, v137, v174
	v_add_f32_e32 v162, v141, v162
	v_exp_f32_e32 v173, v137
	v_add_f32_e32 v162, v140, v162
	v_add_f32_e32 v162, v143, v162
	v_add_f32_e32 v162, v142, v162
	v_sub_f32_e32 v136, v136, v174
	v_add_f32_e32 v137, v173, v162
	v_exp_f32_e32 v162, v136
	v_exp_f32_e32 v136, v138
	v_cvt_pk_bf16_f32 v138, v143, v142
	v_add_f32_e32 v175, v162, v137
	v_fmac_f32_e32 v175, v161, v136
	v_pk_mul_f32 v[42:43], v[42:43], v[136:137] op_sel_hi:[1,0]
	v_pk_mul_f32 v[40:41], v[40:41], v[136:137] op_sel_hi:[1,0]
	v_pk_mul_f32 v[46:47], v[46:47], v[136:137] op_sel_hi:[1,0]
	v_pk_mul_f32 v[44:45], v[44:45], v[136:137] op_sel_hi:[1,0]
	v_pk_mul_f32 v[50:51], v[50:51], v[136:137] op_sel_hi:[1,0]
	v_pk_mul_f32 v[48:49], v[48:49], v[136:137] op_sel_hi:[1,0]
	v_pk_mul_f32 v[54:55], v[54:55], v[136:137] op_sel_hi:[1,0]
	v_pk_mul_f32 v[52:53], v[52:53], v[136:137] op_sel_hi:[1,0]
	v_cvt_pk_bf16_f32 v136, v139, v172
	v_cvt_pk_bf16_f32 v137, v141, v140
	v_cvt_pk_bf16_f32 v139, v173, v162
	v_mov_b32_e32 v161, v175
	v_mov_b32_e32 v162, v174
	v_mfma_f32_16x16x32_bf16 v[40:43], v[116:119], v[136:139], v[40:43]
	v_mfma_f32_16x16x32_bf16 v[44:47], v[112:115], v[136:139], v[44:47]
	v_mfma_f32_16x16x32_bf16 v[48:51], v[108:111], v[136:139], v[48:51]
	v_mfma_f32_16x16x32_bf16 v[52:55], v[104:107], v[136:139], v[52:55]
	s_and_b64 vcc, exec, s[4:5]
	s_cbranch_vccnz .LBB0_263
; #define MFMA16(a, b, c) __builtin_amdgcn_mfma_f32_16x16x32_bf16((a), (b), (c), 0, 0, 0)
; template <int MODE>
; __device__ __forceinline__ void attn_wave(LAS unsigned char* lds, const bf16_t* qkv, bf16_t* Yout, const float* sinks, int wi) {
;     ...
;             f32x4 s[2];
; #pragma unroll
;             for (int nt = 0; nt < 2; ++nt) { f32x4 z = (f32x4){0.f, 0.f, 0.f, 0.f}; z = MFMA16(kf[nt][0], qf[qt][0], z); s[nt] = MFMA16(kf[nt][1], qf[qt][1], z); }
;             const int dbase = q0 + QSTEP * qt + c - k0 - 4 * g;
;             if (MODE == MODE_A) {
;                 float mx = -1e30f;
; #pragma unroll
;                 for (int nt = 0; nt < 2; ++nt)
; #pragma unroll
;                     for (int j = 0; j < 4; ++j) { const int dist = dbase - (16 * nt + j); const bool valid = (unsigned)dist < 128u;
;                         const float bias2 = lutp[qt * HSTEP * 128 + (dist & 127)];
;                         const float lg = valid ? (s[nt][j] * C1 + bias2) : -1e30f; s[nt][j] = lg; mx = fmaxf(mx, lg); }
;                 mx = fmaxf(mx, __shfl_xor(mx, 16)); mx = fmaxf(mx, __shfl_xor(mx, 32));
;                 const float mnew = fmaxf(mrun[qt], mx); const float alpha = __builtin_amdgcn_exp2f(mrun[qt] - mnew); mrun[qt] = mnew;
;                 float ps = 0.f;
; #pragma unroll
;                 for (int nt = 0; nt < 2; ++nt)
; #pragma unroll
;                     for (int j = 0; j < 4; ++j) { const float p = __builtin_amdgcn_exp2f(s[nt][j] - mnew); s[nt][j] = p; ps += p; }
;                 lrun[qt] = lrun[qt] * alpha + ps;
; #pragma unroll
;                 for (int dt = 0; dt < 4; ++dt) o[qt][dt] = o[qt][dt] * alpha;
;             } else {
;                 float lk[2][4], c4[2];
; #pragma unroll
;                 for (int nt = 0; nt < 2; ++nt) { c4[nt] = 0.f;
; #pragma unroll
;                     for (int j = 0; j < 4; ++j) { const bool valid = (dbase - (16 * nt + j)) > 0; const float z = s[nt][j] * C1;
;                         const float e = __builtin_amdgcn_exp2f(-fabsf(z));
;                         const float sp = fmaxf(z, 0.f) + __builtin_amdgcn_logf(1.f + e);
;                         lk[nt][j] = valid ? -sp : 0.f; s[nt][j] = valid ? (z - sp) : -1e30f; c4[nt] += lk[nt][j]; } }
;                 float after = 0.f;
; #pragma unroll
;     ...
;                     const float v1 = __shfl_xor(c4[nt], 16), v2 = __shfl_xor(c4[nt], 32), v3 = __shfl_xor(c4[nt], 48);
.LBB0_298:
	v_mfma_f32_16x16x32_bf16 v[136:139], v[120:123], v[88:91], 0
	v_mfma_f32_16x16x32_bf16 v[140:143], v[124:127], v[92:95], v[136:139]
	v_mfma_f32_16x16x32_bf16 v[136:139], v[132:135], v[88:91], 0
	v_mfma_f32_16x16x32_bf16 v[136:139], v[128:131], v[92:95], v[136:139]
	v_add_u32_e32 v228, s19, v167
	v_add_u32_e32 v228, 0x12400, v228
	ds_read_b32 v228, v228
	v_add_u32_e32 v229, s19, v167
	v_add_u32_e32 v229, 0x123fc, v229
	ds_read_b32 v229, v229
	v_add_u32_e32 v230, s19, v167
	v_add_u32_e32 v230, 0x123f8, v230
	ds_read_b32 v230, v230
	v_add_u32_e32 v231, s19, v167
	v_add_u32_e32 v231, 0x123f4, v231
	ds_read_b32 v231, v231
	v_add_u32_e32 v232, s19, v167
	v_add_u32_e32 v232, 0x123c0, v232
	ds_read_b32 v232, v232
	v_add_u32_e32 v233, s19, v165
	v_add_u32_e32 v233, 0x123bc, v233
	ds_read_b32 v233, v233
	v_add_u32_e32 v234, s19, v165
	v_add_u32_e32 v234, 0x123b8, v234
	ds_read_b32 v234, v234
	v_add_u32_e32 v235, s19, v165
	v_add_u32_e32 v235, 0x123b4, v235
	ds_read_b32 v235, v235
	s_waitcnt lgkmcnt(0)
	v_cmp_gt_u32_e32 vcc, s15, v171
	v_fmac_f32_e32 v228, 0x3e38aa3b, v140
	s_nop 0
	v_cndmask_b32_e32 v173, v226, v228, vcc
	v_add_u32_e32 v236, 30, v170
	v_cmp_gt_u32_e32 vcc, s15, v236
	v_fmac_f32_e32 v229, 0x3e38aa3b, v141
	s_nop 0
	v_cndmask_b32_e32 v172, v226, v229, vcc
	v_add_u32_e32 v236, 29, v170
	v_cmp_gt_u32_e32 vcc, s15, v236
	v_fmac_f32_e32 v230, 0x3e38aa3b, v142
	s_nop 0
	v_cndmask_b32_e32 v141, v226, v230, vcc
	v_add_u32_e32 v236, 28, v170
	v_cmp_gt_u32_e32 vcc, s15, v236
	v_fmac_f32_e32 v231, 0x3e38aa3b, v143
	s_nop 0
	v_cndmask_b32_e32 v140, v226, v231, vcc
	v_add_u32_e32 v236, 15, v170
	v_cmp_gt_u32_e32 vcc, s15, v236
	v_fmac_f32_e32 v232, 0x3e38aa3b, v136
	s_nop 0
	v_cndmask_b32_e32 v143, v226, v232, vcc
	v_add_u32_e32 v236, 14, v170
	v_cmp_gt_u32_e32 vcc, s15, v236
	v_fmac_f32_e32 v233, 0x3e38aa3b, v137
	s_nop 0
	v_cndmask_b32_e32 v142, v226, v233, vcc
	v_add_u32_e32 v236, 13, v170
	v_cmp_gt_u32_e32 vcc, s15, v236
	v_fmac_f32_e32 v234, 0x3e38aa3b, v138
	s_nop 0
	v_cndmask_b32_e32 v137, v226, v234, vcc
	v_add_u32_e32 v236, 12, v170
	v_cmp_gt_u32_e32 vcc, s15, v236
	v_fmac_f32_e32 v235, 0x3e38aa3b, v139
	s_nop 0
	v_cndmask_b32_e32 v136, v226, v235, vcc
	v_max3_f32 v138, v173, s86, v172
	v_max3_f32 v138, v138, v141, v140
	v_cmp_lt_i32_e32 vcc, v223, v218
	v_max3_f32 v138, v138, v143, v142
	v_max3_f32 v138, v138, v137, v136
	v_cndmask_b32_e32 v139, v217, v223, vcc
	v_lshlrev_b32_e32 v139, 2, v139
	ds_bpermute_b32 v139, v139, v138
	v_cmp_lt_i32_e32 vcc, v224, v218
	s_waitcnt lgkmcnt(0)
	v_max_f32_e32 v139, v139, v139
	v_max_f32_e32 v138, v138, v139
	v_cndmask_b32_e32 v139, v217, v224, vcc
	v_lshlrev_b32_e32 v139, 2, v139
	ds_bpermute_b32 v139, v139, v138
	s_waitcnt lgkmcnt(0)
	v_max3_f32 v174, v159, v138, v139
	v_sub_f32_e32 v139, v173, v174
	v_exp_f32_e32 v139, v139
	v_sub_f32_e32 v172, v172, v174
	v_exp_f32_e32 v172, v172
	v_sub_f32_e32 v141, v141, v174
	v_exp_f32_e32 v141, v141
	v_sub_f32_e32 v140, v140, v174
	v_exp_f32_e32 v140, v140
	v_sub_f32_e32 v143, v143, v174
	v_sub_f32_e32 v138, v159, v174
	v_add_f32_e32 v159, 0, v139
	v_exp_f32_e32 v143, v143
	v_sub_f32_e32 v142, v142, v174
	v_add_f32_e32 v159, v172, v159
	v_exp_f32_e32 v142, v142
	v_sub_f32_e32 v137, v137, v174
	v_add_f32_e32 v159, v141, v159
	v_exp_f32_e32 v173, v137
	v_add_f32_e32 v159, v140, v159
	v_add_f32_e32 v159, v143, v159
	v_add_f32_e32 v159, v142, v159
	v_sub_f32_e32 v136, v136, v174
	v_add_f32_e32 v137, v173, v159
	v_exp_f32_e32 v159, v136
	v_exp_f32_e32 v136, v138
	v_cvt_pk_bf16_f32 v138, v143, v142
	v_add_f32_e32 v175, v159, v137
	v_fmac_f32_e32 v175, v158, v136
	v_pk_mul_f32 v[26:27], v[26:27], v[136:137] op_sel_hi:[1,0]
	v_pk_mul_f32 v[24:25], v[24:25], v[136:137] op_sel_hi:[1,0]
	v_pk_mul_f32 v[30:31], v[30:31], v[136:137] op_sel_hi:[1,0]
	v_pk_mul_f32 v[28:29], v[28:29], v[136:137] op_sel_hi:[1,0]
	v_pk_mul_f32 v[34:35], v[34:35], v[136:137] op_sel_hi:[1,0]
	v_pk_mul_f32 v[32:33], v[32:33], v[136:137] op_sel_hi:[1,0]
	v_pk_mul_f32 v[38:39], v[38:39], v[136:137] op_sel_hi:[1,0]
	v_pk_mul_f32 v[36:37], v[36:37], v[136:137] op_sel_hi:[1,0]
	v_cvt_pk_bf16_f32 v136, v139, v172
	v_cvt_pk_bf16_f32 v137, v141, v140
	v_cvt_pk_bf16_f32 v139, v173, v159
	v_mov_b32_e32 v158, v175
	v_mov_b32_e32 v159, v174
	v_mfma_f32_16x16x32_bf16 v[24:27], v[116:119], v[136:139], v[24:27]
	v_mfma_f32_16x16x32_bf16 v[28:31], v[112:115], v[136:139], v[28:31]
	v_mfma_f32_16x16x32_bf16 v[32:35], v[108:111], v[136:139], v[32:35]
	v_mfma_f32_16x16x32_bf16 v[36:39], v[104:107], v[136:139], v[36:39]
	s_and_b64 vcc, exec, s[4:5]
	s_cbranch_vccnz .LBB0_259
.LBB0_315:
	v_mfma_f32_16x16x32_bf16 v[120:123], v[120:123], v[96:99], 0
	v_cmp_gt_u32_e32 vcc, s15, v171
	v_mfma_f32_16x16x32_bf16 v[124:127], v[124:127], v[100:103], v[120:123]
	v_mfma_f32_16x16x32_bf16 v[120:123], v[132:135], v[96:99], 0
	v_mov_b32_e32 v132, 0xf149f2ca
	v_add_u32_e32 v134, s19, v167
	v_mov_b32_e32 v133, 0xf149f2ca
	v_mfma_f32_16x16x32_bf16 v[120:123], v[128:131], v[100:103], v[120:123]
	s_and_saveexec_b64 s[4:5], vcc
	s_cbranch_execz .LBB0_317
	v_add_u32_e32 v128, 0x12600, v134
	ds_read_b32 v133, v128
	s_waitcnt lgkmcnt(0)
	v_fmac_f32_e32 v133, 0x3e38aa3b, v124
